# in-proj K-loop: first two vmcnt waits of each unit after an epilogue ignore the 16 epilogue stores (vmcnt 24)
# speedup vs baseline: 1.0007x; 1.0006x over previous
.LBB0_645:
	s_add_u32 s37, s42, 0xfffc0080
	s_addc_u32 s39, s43, -1
	s_add_i32 s65, 0, 0x10000
	s_cmp_eq_u32 s64, 12
	s_cselect_b32 s63, s0, s39
	s_cselect_b32 s62, s1, s37
	v_add_u32_e32 v145, s65, v162
	s_cselect_b32 s45, s20, s30
	s_cselect_b32 s44, s21, s22
	s_add_i32 s37, 0, 0x14000
	ds_read_b128 v[146:149], v145
	ds_read_b128 v[150:153], v145 offset:1024
	ds_read_b128 v[154:157], v145 offset:2048
	ds_read_b128 v[170:173], v145 offset:3072
	v_add_u32_e32 v145, s37, v162
	ds_read_b128 v[178:181], v145
	ds_read_b128 v[182:185], v145 offset:1024
	ds_read_b128 v[186:189], v145 offset:2048
	ds_read_b128 v[208:211], v145 offset:3072
	v_lshl_add_u64 v[158:159], s[42:43], 0, v[140:141]
	s_add_i32 m0, s56, 0xc000
	ds_read_b128 v[212:215], v168
	ds_read_b128 v[216:219], v168 offset:1024
	ds_read_b128 v[220:223], v168 offset:2048
	ds_read_b128 v[224:227], v168 offset:3072
	ds_read_b128 v[228:231], v168 offset:4096
	ds_read_b128 v[232:235], v168 offset:5120
	ds_read_b128 v[236:239], v168 offset:6144
	ds_read_b128 v[240:243], v168 offset:7168
	global_load_lds_dwordx4 v[158:159], off
	v_lshl_add_u64 v[158:159], s[42:43], 0, v[142:143]
	s_add_i32 m0, s56, 0xe000
	s_nop 0
	global_load_lds_dwordx4 v[158:159], off
	s_cmp_eq_u32 s64, -2
	s_cbranch_scc0 .Lrw8_ip0
	s_cmp_gt_u32 s35, 1
	s_cbranch_scc0 .Lrw8_ip0
	s_waitcnt vmcnt(24)
	s_branch .Lrwd_ip0
.Lrw8_ip0:
	s_waitcnt vmcnt(8)
.Lrwd_ip0:
	s_waitcnt lgkmcnt(0)
	s_barrier
	s_setprio 1
	s_waitcnt lgkmcnt(0)
	v_mfma_f32_16x16x32_bf16 v[124:127], v[146:149], v[212:215], v[124:127]
	v_mfma_f32_16x16x32_bf16 v[120:123], v[154:157], v[212:215], v[120:123]
	v_mfma_f32_16x16x32_bf16 v[116:119], v[146:149], v[220:223], v[116:119]
	v_mfma_f32_16x16x32_bf16 v[112:115], v[154:157], v[220:223], v[112:115]
	v_mfma_f32_16x16x32_bf16 v[100:103], v[146:149], v[228:231], v[100:103]
	v_mfma_f32_16x16x32_bf16 v[96:99], v[154:157], v[228:231], v[96:99]
	v_mfma_f32_16x16x32_bf16 v[84:87], v[146:149], v[236:239], v[84:87]
	v_mfma_f32_16x16x32_bf16 v[80:83], v[154:157], v[236:239], v[80:83]
	v_mfma_f32_16x16x32_bf16 v[124:127], v[150:153], v[216:219], v[124:127]
	v_mfma_f32_16x16x32_bf16 v[120:123], v[170:173], v[216:219], v[120:123]
	v_mfma_f32_16x16x32_bf16 v[116:119], v[150:153], v[224:227], v[116:119]
	v_mfma_f32_16x16x32_bf16 v[112:115], v[170:173], v[224:227], v[112:115]
	v_mfma_f32_16x16x32_bf16 v[100:103], v[150:153], v[232:235], v[100:103]
	v_mfma_f32_16x16x32_bf16 v[96:99], v[170:173], v[232:235], v[96:99]
	v_mfma_f32_16x16x32_bf16 v[84:87], v[150:153], v[240:243], v[84:87]
	v_mfma_f32_16x16x32_bf16 v[80:83], v[170:173], v[240:243], v[80:83]
	s_setprio 0
	s_setprio 1
	v_mfma_f32_16x16x32_bf16 v[108:111], v[178:181], v[212:215], v[108:111]
	v_mfma_f32_16x16x32_bf16 v[104:107], v[186:189], v[212:215], v[104:107]
	v_mfma_f32_16x16x32_bf16 v[92:95], v[178:181], v[220:223], v[92:95]
	v_mfma_f32_16x16x32_bf16 v[88:91], v[186:189], v[220:223], v[88:91]
	v_mfma_f32_16x16x32_bf16 v[76:79], v[178:181], v[228:231], v[76:79]
	v_mfma_f32_16x16x32_bf16 v[72:75], v[186:189], v[228:231], v[72:75]
	v_mfma_f32_16x16x32_bf16 v[68:71], v[178:181], v[236:239], v[68:71]
	v_mfma_f32_16x16x32_bf16 v[64:67], v[186:189], v[236:239], v[64:67]
	v_mfma_f32_16x16x32_bf16 v[108:111], v[182:185], v[216:219], v[108:111]
	v_mfma_f32_16x16x32_bf16 v[104:107], v[208:211], v[216:219], v[104:107]
	v_mfma_f32_16x16x32_bf16 v[92:95], v[182:185], v[224:227], v[92:95]
	v_mfma_f32_16x16x32_bf16 v[88:91], v[208:211], v[224:227], v[88:91]
	v_mfma_f32_16x16x32_bf16 v[76:79], v[182:185], v[232:235], v[76:79]
	v_mfma_f32_16x16x32_bf16 v[72:75], v[208:211], v[232:235], v[72:75]
	v_mfma_f32_16x16x32_bf16 v[68:71], v[182:185], v[240:243], v[68:71]
	v_mfma_f32_16x16x32_bf16 v[64:67], v[208:211], v[240:243], v[64:67]
	s_setprio 0
	s_barrier
	s_add_i32 s39, s65, s52
	v_lshl_add_u64 v[158:159], s[44:45], 0, v[132:133]
	s_mov_b32 m0, s39
	ds_read_b128 v[212:215], v168 offset:16384
	ds_read_b128 v[216:219], v168 offset:17408
	ds_read_b128 v[220:223], v168 offset:18432
	ds_read_b128 v[224:227], v168 offset:19456
	ds_read_b128 v[228:231], v168 offset:20480
	ds_read_b128 v[232:235], v168 offset:21504
	ds_read_b128 v[236:239], v168 offset:22528
	ds_read_b128 v[240:243], v168 offset:23552
	global_load_lds_dwordx4 v[158:159], off
	s_add_i32 m0, s39, 0x2000
	s_add_u32 s66, s44, 0x10000
	v_lshl_add_u64 v[174:175], s[44:45], 0, v[128:129]
	s_addc_u32 s67, s45, 0
	s_add_i32 s37, s37, s52
	global_load_lds_dwordx4 v[174:175], off
	v_lshl_add_u64 v[244:245], s[66:67], 0, v[132:133]
	s_mov_b32 m0, s37
	v_lshl_add_u64 v[246:247], s[62:63], 0, v[130:131]
	global_load_lds_dwordx4 v[244:245], off
	v_lshl_add_u64 v[244:245], s[66:67], 0, v[128:129]
	s_add_i32 m0, s37, 0x2000
	s_nop 0
	global_load_lds_dwordx4 v[244:245], off
	v_lshl_add_u64 v[244:245], s[62:63], 0, v[134:135]
	s_mov_b32 m0, s56
	s_nop 0
	global_load_lds_dwordx4 v[244:245], off
	s_mov_b32 m0, s57
	s_nop 0
	global_load_lds_dwordx4 v[246:247], off
	s_cmp_eq_u32 s64, -2
	s_cbranch_scc0 .Lrw8_ip1
	s_cmp_gt_u32 s35, 1
	s_cbranch_scc0 .Lrw8_ip1
	s_waitcnt vmcnt(24)
	s_branch .Lrwd_ip1

.Lrwd_ip1:
	s_waitcnt lgkmcnt(0)
	s_barrier
	s_setprio 1
	s_waitcnt lgkmcnt(0)
	v_mfma_f32_16x16x32_bf16 v[60:63], v[146:149], v[212:215], v[60:63]
	v_mfma_f32_16x16x32_bf16 v[56:59], v[154:157], v[212:215], v[56:59]
	v_mfma_f32_16x16x32_bf16 v[52:55], v[146:149], v[220:223], v[52:55]
	v_mfma_f32_16x16x32_bf16 v[48:51], v[154:157], v[220:223], v[48:51]
	v_mfma_f32_16x16x32_bf16 v[36:39], v[146:149], v[228:231], v[36:39]
	v_mfma_f32_16x16x32_bf16 v[32:35], v[154:157], v[228:231], v[32:35]
	v_mfma_f32_16x16x32_bf16 v[20:23], v[146:149], v[236:239], v[20:23]
	v_mfma_f32_16x16x32_bf16 v[16:19], v[154:157], v[236:239], v[16:19]
	v_mfma_f32_16x16x32_bf16 v[60:63], v[150:153], v[216:219], v[60:63]
	v_mfma_f32_16x16x32_bf16 v[56:59], v[170:173], v[216:219], v[56:59]
	v_mfma_f32_16x16x32_bf16 v[52:55], v[150:153], v[224:227], v[52:55]
	v_mfma_f32_16x16x32_bf16 v[48:51], v[170:173], v[224:227], v[48:51]
	v_mfma_f32_16x16x32_bf16 v[36:39], v[150:153], v[232:235], v[36:39]
	v_mfma_f32_16x16x32_bf16 v[32:35], v[170:173], v[232:235], v[32:35]
	v_mfma_f32_16x16x32_bf16 v[20:23], v[150:153], v[240:243], v[20:23]
	v_mfma_f32_16x16x32_bf16 v[16:19], v[170:173], v[240:243], v[16:19]
	s_setprio 0
	s_setprio 1
	v_mfma_f32_16x16x32_bf16 v[44:47], v[178:181], v[212:215], v[44:47]
	v_mfma_f32_16x16x32_bf16 v[40:43], v[186:189], v[212:215], v[40:43]
	v_mfma_f32_16x16x32_bf16 v[28:31], v[178:181], v[220:223], v[28:31]
	v_mfma_f32_16x16x32_bf16 v[24:27], v[186:189], v[220:223], v[24:27]
	v_mfma_f32_16x16x32_bf16 v[12:15], v[178:181], v[228:231], v[12:15]
	v_mfma_f32_16x16x32_bf16 v[8:11], v[186:189], v[228:231], v[8:11]
	v_mfma_f32_16x16x32_bf16 v[4:7], v[178:181], v[236:239], v[4:7]
	v_mfma_f32_16x16x32_bf16 v[0:3], v[186:189], v[236:239], v[0:3]
	v_mfma_f32_16x16x32_bf16 v[44:47], v[182:185], v[216:219], v[44:47]
	v_mfma_f32_16x16x32_bf16 v[40:43], v[208:211], v[216:219], v[40:43]
	v_mfma_f32_16x16x32_bf16 v[28:31], v[182:185], v[224:227], v[28:31]
	v_mfma_f32_16x16x32_bf16 v[24:27], v[208:211], v[224:227], v[24:27]
	v_mfma_f32_16x16x32_bf16 v[12:15], v[182:185], v[232:235], v[12:15]
	v_mfma_f32_16x16x32_bf16 v[8:11], v[208:211], v[232:235], v[8:11]
	v_mfma_f32_16x16x32_bf16 v[4:7], v[182:185], v[240:243], v[4:7]
	v_mfma_f32_16x16x32_bf16 v[0:3], v[208:211], v[240:243], v[0:3]
	s_setprio 0
	s_barrier
	s_add_i32 s37, 0, 0x18000
	v_add_u32_e32 v145, s37, v162
	s_add_i32 s39, 0, 0x1c000
	ds_read_b128 v[146:149], v145
	ds_read_b128 v[150:153], v145 offset:1024
	ds_read_b128 v[154:157], v145 offset:2048
	ds_read_b128 v[170:173], v145 offset:3072
	v_add_u32_e32 v145, s39, v162
	ds_read_b128 v[178:181], v145
	ds_read_b128 v[182:185], v145 offset:1024
	ds_read_b128 v[186:189], v145 offset:2048
	ds_read_b128 v[208:211], v145 offset:3072
	s_add_u32 s62, s62, 0x40000
	s_addc_u32 s63, s63, 0
	s_mov_b32 m0, s54
	v_lshl_add_u64 v[248:249], s[62:63], 0, v[134:135]
	ds_read_b128 v[212:215], v168 offset:32768
	ds_read_b128 v[216:219], v168 offset:33792
	ds_read_b128 v[220:223], v168 offset:34816
	ds_read_b128 v[224:227], v168 offset:35840
	ds_read_b128 v[228:231], v168 offset:36864
	ds_read_b128 v[232:235], v168 offset:37888
	ds_read_b128 v[236:239], v168 offset:38912
	ds_read_b128 v[240:243], v168 offset:39936
	global_load_lds_dwordx4 v[248:249], off
	v_lshl_add_u64 v[248:249], s[62:63], 0, v[130:131]
	s_mov_b32 m0, s55
	s_nop 0
	global_load_lds_dwordx4 v[248:249], off
	s_waitcnt vmcnt(8)
	s_waitcnt lgkmcnt(0)
	s_barrier
	s_setprio 1
	s_waitcnt lgkmcnt(0)
	v_mfma_f32_16x16x32_bf16 v[124:127], v[146:149], v[212:215], v[124:127]
	v_mfma_f32_16x16x32_bf16 v[120:123], v[154:157], v[212:215], v[120:123]
	v_mfma_f32_16x16x32_bf16 v[116:119], v[146:149], v[220:223], v[116:119]
	v_mfma_f32_16x16x32_bf16 v[112:115], v[154:157], v[220:223], v[112:115]
	v_mfma_f32_16x16x32_bf16 v[100:103], v[146:149], v[228:231], v[100:103]
	v_mfma_f32_16x16x32_bf16 v[96:99], v[154:157], v[228:231], v[96:99]
	v_mfma_f32_16x16x32_bf16 v[84:87], v[146:149], v[236:239], v[84:87]
	v_mfma_f32_16x16x32_bf16 v[80:83], v[154:157], v[236:239], v[80:83]
	v_mfma_f32_16x16x32_bf16 v[124:127], v[150:153], v[216:219], v[124:127]
	v_mfma_f32_16x16x32_bf16 v[120:123], v[170:173], v[216:219], v[120:123]
	v_mfma_f32_16x16x32_bf16 v[116:119], v[150:153], v[224:227], v[116:119]
	v_mfma_f32_16x16x32_bf16 v[112:115], v[170:173], v[224:227], v[112:115]
	v_mfma_f32_16x16x32_bf16 v[100:103], v[150:153], v[232:235], v[100:103]
	v_mfma_f32_16x16x32_bf16 v[96:99], v[170:173], v[232:235], v[96:99]
	v_mfma_f32_16x16x32_bf16 v[84:87], v[150:153], v[240:243], v[84:87]
	v_mfma_f32_16x16x32_bf16 v[80:83], v[170:173], v[240:243], v[80:83]
	s_setprio 0
	s_setprio 1
	v_mfma_f32_16x16x32_bf16 v[108:111], v[178:181], v[212:215], v[108:111]
	v_mfma_f32_16x16x32_bf16 v[104:107], v[186:189], v[212:215], v[104:107]
	v_mfma_f32_16x16x32_bf16 v[92:95], v[178:181], v[220:223], v[92:95]
	v_mfma_f32_16x16x32_bf16 v[88:91], v[186:189], v[220:223], v[88:91]
	v_mfma_f32_16x16x32_bf16 v[76:79], v[178:181], v[228:231], v[76:79]
	v_mfma_f32_16x16x32_bf16 v[72:75], v[186:189], v[228:231], v[72:75]
	v_mfma_f32_16x16x32_bf16 v[68:71], v[178:181], v[236:239], v[68:71]
	v_mfma_f32_16x16x32_bf16 v[64:67], v[186:189], v[236:239], v[64:67]
	v_mfma_f32_16x16x32_bf16 v[108:111], v[182:185], v[216:219], v[108:111]
	v_mfma_f32_16x16x32_bf16 v[104:107], v[208:211], v[216:219], v[104:107]
	v_mfma_f32_16x16x32_bf16 v[92:95], v[182:185], v[224:227], v[92:95]
	v_mfma_f32_16x16x32_bf16 v[88:91], v[208:211], v[224:227], v[88:91]
	v_mfma_f32_16x16x32_bf16 v[76:79], v[182:185], v[232:235], v[76:79]
	v_mfma_f32_16x16x32_bf16 v[72:75], v[208:211], v[232:235], v[72:75]
	v_mfma_f32_16x16x32_bf16 v[68:71], v[182:185], v[240:243], v[68:71]
	v_mfma_f32_16x16x32_bf16 v[64:67], v[208:211], v[240:243], v[64:67]
	s_setprio 0
	s_barrier
	s_add_i32 s37, s37, s52
	v_lshl_add_u64 v[158:159], v[158:159], 0, s[26:27]
	s_mov_b32 m0, s37
	ds_read_b128 v[212:215], v168 offset:49152
	ds_read_b128 v[216:219], v168 offset:50176
	ds_read_b128 v[220:223], v168 offset:51200
	ds_read_b128 v[224:227], v168 offset:52224
	ds_read_b128 v[228:231], v168 offset:53248
	ds_read_b128 v[232:235], v168 offset:54272
	ds_read_b128 v[236:239], v168 offset:55296
	ds_read_b128 v[240:243], v168 offset:56320
	global_load_lds_dwordx4 v[158:159], off
	s_add_i32 m0, s37, 0x2000
	s_add_u32 s44, s44, 0x10080
	v_lshl_add_u64 v[158:159], v[174:175], 0, s[26:27]
	s_addc_u32 s45, s45, 0
	s_add_i32 s37, s39, s52
	global_load_lds_dwordx4 v[158:159], off
	v_lshl_add_u64 v[158:159], s[44:45], 0, v[132:133]
	s_mov_b32 m0, s37
	s_nop 0
	global_load_lds_dwordx4 v[158:159], off
	v_lshl_add_u64 v[158:159], s[44:45], 0, v[128:129]
	s_add_i32 m0, s37, 0x2000
	s_nop 0
	global_load_lds_dwordx4 v[158:159], off
	v_lshl_add_u64 v[158:159], v[244:245], 0, s[26:27]
	s_mov_b32 m0, s34
	s_nop 0
	global_load_lds_dwordx4 v[158:159], off
	v_lshl_add_u64 v[158:159], v[246:247], 0, s[26:27]
	s_mov_b32 m0, s53
	s_nop 0
	global_load_lds_dwordx4 v[158:159], off
	s_waitcnt vmcnt(8)
	s_waitcnt lgkmcnt(0)
	s_barrier
	s_setprio 1
	s_waitcnt lgkmcnt(0)
	v_mfma_f32_16x16x32_bf16 v[60:63], v[146:149], v[212:215], v[60:63]
	v_mfma_f32_16x16x32_bf16 v[56:59], v[154:157], v[212:215], v[56:59]
	v_mfma_f32_16x16x32_bf16 v[52:55], v[146:149], v[220:223], v[52:55]
	v_mfma_f32_16x16x32_bf16 v[48:51], v[154:157], v[220:223], v[48:51]
	v_mfma_f32_16x16x32_bf16 v[36:39], v[146:149], v[228:231], v[36:39]
	v_mfma_f32_16x16x32_bf16 v[32:35], v[154:157], v[228:231], v[32:35]
	v_mfma_f32_16x16x32_bf16 v[20:23], v[146:149], v[236:239], v[20:23]
	v_mfma_f32_16x16x32_bf16 v[16:19], v[154:157], v[236:239], v[16:19]
	v_mfma_f32_16x16x32_bf16 v[60:63], v[150:153], v[216:219], v[60:63]
	v_mfma_f32_16x16x32_bf16 v[56:59], v[170:173], v[216:219], v[56:59]
	v_mfma_f32_16x16x32_bf16 v[52:55], v[150:153], v[224:227], v[52:55]
	v_mfma_f32_16x16x32_bf16 v[48:51], v[170:173], v[224:227], v[48:51]
	v_mfma_f32_16x16x32_bf16 v[36:39], v[150:153], v[232:235], v[36:39]
	v_mfma_f32_16x16x32_bf16 v[32:35], v[170:173], v[232:235], v[32:35]
	v_mfma_f32_16x16x32_bf16 v[20:23], v[150:153], v[240:243], v[20:23]
	v_mfma_f32_16x16x32_bf16 v[16:19], v[170:173], v[240:243], v[16:19]
	s_setprio 0
	s_setprio 1
	v_mfma_f32_16x16x32_bf16 v[44:47], v[178:181], v[212:215], v[44:47]
	v_mfma_f32_16x16x32_bf16 v[40:43], v[186:189], v[212:215], v[40:43]
	v_mfma_f32_16x16x32_bf16 v[28:31], v[178:181], v[220:223], v[28:31]
	v_mfma_f32_16x16x32_bf16 v[24:27], v[186:189], v[220:223], v[24:27]
	v_mfma_f32_16x16x32_bf16 v[12:15], v[178:181], v[228:231], v[12:15]
	v_mfma_f32_16x16x32_bf16 v[8:11], v[186:189], v[228:231], v[8:11]
	v_mfma_f32_16x16x32_bf16 v[4:7], v[178:181], v[236:239], v[4:7]
	v_mfma_f32_16x16x32_bf16 v[0:3], v[186:189], v[236:239], v[0:3]
	v_mfma_f32_16x16x32_bf16 v[44:47], v[182:185], v[216:219], v[44:47]
	v_mfma_f32_16x16x32_bf16 v[40:43], v[208:211], v[216:219], v[40:43]
	v_mfma_f32_16x16x32_bf16 v[28:31], v[182:185], v[224:227], v[28:31]
	v_mfma_f32_16x16x32_bf16 v[24:27], v[208:211], v[224:227], v[24:27]
	v_mfma_f32_16x16x32_bf16 v[12:15], v[182:185], v[232:235], v[12:15]
	v_mfma_f32_16x16x32_bf16 v[8:11], v[208:211], v[232:235], v[8:11]
	v_mfma_f32_16x16x32_bf16 v[4:7], v[182:185], v[240:243], v[4:7]
	v_mfma_f32_16x16x32_bf16 v[0:3], v[208:211], v[240:243], v[0:3]
	s_setprio 0
	s_barrier
	s_add_i32 s64, s64, 2
	s_add_u32 s42, s42, 0x100
	s_addc_u32 s43, s43, 0
	s_add_u32 s22, s22, 0x100
	s_addc_u32 s30, s30, 0
	s_cmp_gt_u32 s64, 13
	s_cbranch_scc0 .LBB0_645
	v_readlane_b32 s0, v252, 26
	v_readlane_b32 s1, v252, 27
	s_and_b64 vcc, exec, s[0:1]
	v_readlane_b32 s68, v252, 11
	v_readlane_b32 s69, v252, 12
	s_cbranch_vccz .LBB0_648
	s_barrier
